# v24: v22 + prompt sliding-window attention requests V of the next tile together with K (second V buffer + moves)
# baseline (speedup 1.0000x reference)
; DI float fexp2(float x) { return __builtin_amdgcn_exp2f(x); }
; DI bf16x8 pack_step(const f32x16& x, int s) { u32x4 p; p.x = pk2(x[8 * s], x[8 * s + 1]); p.y = pk2(x[8 * s + 2], x[8 * s + 3]); p.z = pk2(x[8 * s + 4], x[8 * s + 5]); p.w = pk2(x[8 * s + 6], x[8 * s + 7]); return __builtin_bit_cast(bf16x8, p); }
; #define MFMA32(a, b, c) __builtin_amdgcn_mfma_f32_32x32x16_bf16((a), (b), (c), 0, 0, 0)
;     DI bf16x8 kfrag_t(int tl, int kk) const { const int lane = threadIdx.x & 63; return ld8f_bf(krow(ck, nk, 32 * tl + (lane & 31)) + 16 * kk + 8 * (lane >> 5)); }
;     DI bf16x8 kfrag_t(int tl, int kk) const { const int lane = threadIdx.x & 63; return ld8f_bf(mk + ((size_t)(b * 256 + 32 * tl + (lane & 31)) * 4 + hd) * 128 + 16 * kk + 8 * (lane >> 5)); }
; template <class T> DI void attn_item(const T& t) {
;     ...
;     for (int kk = 0; kk < D / 16; ++kk) qf[kk] = t.qfrag(r, 16 * kk + 8 * h);
;     const int cbeg = t.cbeg();
;     if (!T::VSPLIT) {
; #pragma unroll
;         for (int kk = 0; kk < D / 16; ++kk) kf[kk] = t.kfrag_t(t.tile(cbeg), kk);
;     }
;     float m = t.m_init(r), l = t.l_init();
;     f32x16 o[D / 32];
; #pragma unroll
;     for (int dd = 0; dd < D / 32; ++dd)
; #pragma unroll
;         for (int i = 0; i < 16; ++i) o[dd][i] = 0.f;
;     bf16x8 vf[2][D / 32];
;     ...
;         float ps = 0.f;
; #pragma unroll
;         for (int i = 0; i < 16; ++i) { const float p = fexp2(s[i] - m); s[i] = p; ps += p; }
;         ps += __shfl_xor(ps, 32);
;         l += ps;
; #pragma unroll
;         for (int s2 = 0; s2 < 2; ++s2) { const bf16x8 pb = pack_step(s, s2);
;             if (T::VSPLIT) {
; #pragma unroll
;                 for (int dd = 0; dd < D / 32; ++dd) vf[s2][dd] = t.vfrag_t(tl, s2, dd);
;             }
; #pragma unroll
;             for (int dd = 0; dd < D / 32; ++dd) o[dd] = MFMA32(vf[s2][dd], pb, o[dd]); }
.LBB0_968:
	s_mulk_i32 s72, 0xf10
	s_add_i32 s78, s76, s72
	s_cmpk_gt_i32 s78, 0x2327
	s_mov_b64 s[40:41], -1
	s_cbranch_scc1 .LBB0_959
	s_cmpk_gt_i32 s78, 0xfff
	v_lshlrev_b32_e32 v2, 1, v184
	s_cbranch_scc0 .LBB0_980
	s_add_i32 s40, s78, 0xfffff000
	s_lshr_b32 s88, s40, 10
	s_and_b32 s41, s78, 0x7f
	s_lshl_b32 s72, s88, 12
	s_lshl_b32 s40, s41, 5
	s_or_b32 s72, s72, s40
	v_or_b32_e32 v4, s72, v1
	s_bfe_u32 s85, s78, 0x30007
	v_mul_lo_u32 v4, v4, s59
	v_mov_b32_e32 v5, v3
	v_lshl_add_u64 v[4:5], v[4:5], 1, s[48:49]
	s_lshl_b32 s72, s85, 7
	s_load_dwordx2 s[86:87], s[0:1], 0x70
	v_lshl_add_u64 v[100:101], v[4:5], 0, s[72:73]
	s_lshl_b32 s72, s78, 10
	s_and_b32 s72, s72, 0x80000
	s_lshl_b32 s88, s88, 20
	s_or_b32 s72, s88, s72
	s_lshl_b32 s88, s85, 2
	v_mov_b32_e32 v4, s88
	v_lshl_add_u64 v[6:7], v[100:101], 0, v[2:3]
	s_waitcnt lgkmcnt(0)
	global_load_dword v9, v4, s[86:87]
	global_load_dwordx4 v[52:55], v[6:7], off
	global_load_dwordx4 v[56:59], v[6:7], off offset:32
	global_load_dwordx4 v[60:63], v[6:7], off offset:64
	global_load_dwordx4 v[64:67], v[6:7], off offset:96
	v_sub_u32_e64 v6, 4, s41 clamp
	v_add_u32_e32 v6, s41, v6
	v_add_u32_e32 v6, -4, v6
	v_ashrrev_i32_e32 v7, 31, v6
	v_lshl_add_u64 v[4:5], v[188:189], 0, s[72:73]
	v_lshlrev_b64 v[6:7], 12, v[6:7]
	v_lshl_add_u64 v[4:5], v[4:5], 0, v[6:7]
	global_load_dwordx4 v[80:83], v[4:5], off offset:3072
	global_load_dwordx4 v[76:79], v[4:5], off offset:2048
	global_load_dwordx4 v[72:75], v[4:5], off offset:1024
	global_load_dwordx4 v[68:71], v[4:5], off
	s_lshl_b32 s79, s79, 4
	s_lshl_b32 s86, s77, 4
	s_add_i32 s79, s79, s76
	s_sub_i32 s76, s79, s86
	s_mov_b32 s77, s73
	s_and_b32 s76, s76, 0x7f
	v_and_b32_e32 v11, 64, v185
	s_add_i32 s85, s85, 1
	v_cmp_lt_u64_e64 s[86:87], s[76:77], 4
	v_xor_b32_e32 v10, 32, v185
	v_add_u32_e32 v11, 64, v11
	v_cvt_f32_ubyte0_e32 v12, s85
	s_and_b64 s[86:87], s[86:87], exec
	v_or_b32_e32 v13, s40, v1
	v_cmp_lt_i32_e32 vcc, v10, v11
	v_exp_f32_e64 v11, -v12
	s_cselect_b32 s76, s76, 4
	s_min_u32 s87, s41, 4
	v_cvt_f32_u32_e32 v12, v13
	s_lshl_b32 s79, s76, 12
	s_sub_i32 s76, s41, s87
	s_ashr_i32 s77, s76, 31
	s_add_u32 s85, s79, 0xffffc000
	s_add_u32 s86, s79, 0x1000
	s_lshl_b64 s[76:77], s[76:77], 12
	v_cndmask_b32_e32 v10, v185, v10, vcc
	v_mul_f32_e32 v102, 0x3fb8aa3b, v11
	s_add_u32 s76, s76, s72
	v_mov_b32_e32 v18, v3
	v_mov_b32_e32 v19, v3
	v_mov_b32_e32 v4, v3
	v_mov_b32_e32 v5, v3
	v_mov_b32_e32 v6, v3
	v_mov_b32_e32 v7, v3
	v_mov_b32_e32 v8, v3
	v_lshlrev_b32_e32 v103, 2, v10
	v_mul_f32_e32 v124, v102, v12
	s_addc_u32 s77, s77, 0
	s_lshl_b32 s41, s87, 5
	v_mov_b32_e32 v10, v3
	v_mov_b32_e32 v11, v3
	v_mov_b32_e32 v12, v3
	v_mov_b32_e32 v13, v3
	v_mov_b32_e32 v14, v3
	v_mov_b32_e32 v15, v3
	v_mov_b32_e32 v16, v3
	v_mov_b32_e32 v17, v3
	v_pk_mul_f32 v[104:105], v[102:103], v[190:191] op_sel_hi:[0,1]
	v_pk_mul_f32 v[106:107], v[102:103], v[192:193] op_sel_hi:[0,1]
	v_pk_mul_f32 v[108:109], v[102:103], v[194:195] op_sel_hi:[0,1]
	v_pk_mul_f32 v[110:111], v[102:103], v[196:197] op_sel_hi:[0,1]
	v_pk_mul_f32 v[112:113], v[102:103], v[198:199] op_sel_hi:[0,1]
	v_pk_mul_f32 v[114:115], v[102:103], v[200:201] op_sel_hi:[0,1]
	v_pk_mul_f32 v[116:117], v[102:103], v[202:203] op_sel_hi:[0,1]
	v_pk_mul_f32 v[118:119], v[102:103], v[204:205] op_sel_hi:[0,1]
	v_lshl_add_u64 v[120:121], v[208:209], 0, s[76:77]
	s_sub_i32 s72, s40, s41
	v_lshl_add_u64 v[122:123], v[212:213], 0, s[76:77]
	v_mov_b32_e32 v125, 1.0
	s_mov_b64 s[40:41], 0
	s_waitcnt vmcnt(8)
	v_mul_f32_e32 v126, 0x3fb8aa3b, v9
	v_mov_b32_e32 v9, v3
	v_mov_b64_e32 v[34:35], v[18:19]
	v_mov_b64_e32 v[32:33], v[16:17]
	v_mov_b64_e32 v[30:31], v[14:15]
	v_mov_b64_e32 v[28:29], v[12:13]
	v_mov_b64_e32 v[26:27], v[10:11]
	v_mov_b64_e32 v[24:25], v[8:9]
	v_mov_b64_e32 v[22:23], v[6:7]
	v_mov_b64_e32 v[20:21], v[4:5]
	v_lshl_add_u64 v[84:85], v[120:121], 0, s[40:41]
	global_load_dwordx4 v[96:99], v[84:85], off offset:-2048
	global_load_dwordx4 v[92:95], v[84:85], off offset:-1536
	global_load_dwordx4 v[88:91], v[84:85], off
	s_nop 0
	global_load_dwordx4 v[84:87], v[84:85], off offset:512
	s_branch .LBB0_972
.LBB0_971:
	s_cmp_eq_u32 s79, s40
	s_cbranch_scc1 .Latt_sw3_last
	v_sub_f32_e32 v36, v36, v126
	v_exp_f32_e32 v36, v36
	v_sub_f32_e32 v37, v37, v126
	v_exp_f32_e32 v37, v37
	v_sub_f32_e32 v38, v38, v126
	v_exp_f32_e32 v38, v38
	v_sub_f32_e32 v39, v39, v126
	v_exp_f32_e32 v39, v39
	v_sub_f32_e32 v40, v40, v126
	v_add_f32_e32 v127, 0, v36
	v_exp_f32_e32 v40, v40
	v_sub_f32_e32 v41, v41, v126
	v_add_f32_e32 v127, v37, v127
	v_exp_f32_e32 v41, v41
	v_sub_f32_e32 v42, v42, v126
	v_sub_f32_e32 v43, v43, v126
	v_add_f32_e32 v127, v38, v127
	v_exp_f32_e32 v42, v42
	v_exp_f32_e32 v43, v43
	v_add_f32_e32 v127, v39, v127
	v_sub_f32_e32 v44, v44, v126
	v_add_f32_e32 v127, v40, v127
	v_exp_f32_e32 v44, v44
	v_sub_f32_e32 v45, v45, v126
	v_add_f32_e32 v127, v41, v127
	v_exp_f32_e32 v45, v45
	v_sub_f32_e32 v46, v46, v126
	v_add_f32_e32 v127, v42, v127
	v_exp_f32_e32 v46, v46
	v_sub_f32_e32 v47, v47, v126
	v_cvt_pk_bf16_f32 v36, v36, v37
	v_cvt_pk_bf16_f32 v37, v38, v39
	v_cvt_pk_bf16_f32 v38, v40, v41
	v_cvt_pk_bf16_f32 v39, v42, v43
	v_add_f32_e32 v127, v43, v127
	v_exp_f32_e32 v47, v47
	v_sub_f32_e32 v48, v48, v126
	s_waitcnt vmcnt(11)
	v_mfma_f32_32x32x16_bf16 v[20:35], v[96:99], v[36:39], v[20:35]
	v_add_f32_e32 v127, v44, v127
	v_exp_f32_e32 v40, v48
	v_sub_f32_e32 v41, v49, v126
	v_add_f32_e32 v127, v45, v127
	v_exp_f32_e32 v41, v41
	v_sub_f32_e32 v42, v50, v126
	v_add_f32_e32 v127, v46, v127
	s_waitcnt vmcnt(10)
	v_mfma_f32_32x32x16_bf16 v[4:19], v[92:95], v[36:39], v[4:19]
	v_sub_f32_e32 v36, v51, v126
	v_exp_f32_e32 v42, v42
	v_exp_f32_e32 v48, v36
	v_add_f32_e32 v127, v47, v127
	v_add_f32_e32 v43, v40, v127
	v_add_f32_e32 v43, v41, v43
	v_add_f32_e32 v43, v42, v43
	v_cvt_pk_bf16_f32 v36, v44, v45
	v_cvt_pk_bf16_f32 v37, v46, v47
	v_cvt_pk_bf16_f32 v38, v40, v41
	v_cvt_pk_bf16_f32 v39, v42, v48
	v_add_f32_e32 v40, v48, v43
	ds_bpermute_b32 v41, v103, v40
	s_waitcnt vmcnt(9)
	v_mfma_f32_32x32x16_bf16 v[20:35], v[88:91], v[36:39], v[20:35]
	s_add_u32 s40, s40, 0x1000
	s_addc_u32 s41, s41, 0
	s_add_i32 s72, s72, 32
	s_waitcnt lgkmcnt(0)
	v_add_f32_e32 v40, v40, v41
	s_cmp_eq_u32 s86, s40
	v_add_f32_e32 v125, v125, v40
	s_waitcnt vmcnt(8)
	v_mfma_f32_32x32x16_bf16 v[4:19], v[84:87], v[36:39], v[4:19]
	s_waitcnt vmcnt(0)
	s_nop 7
	v_mov_b64_e32 v[98:99], v[144:145]
	v_mov_b64_e32 v[96:97], v[142:143]
	v_mov_b64_e32 v[94:95], v[140:141]
	v_mov_b64_e32 v[92:93], v[138:139]
	v_mov_b64_e32 v[90:91], v[136:137]
	v_mov_b64_e32 v[88:89], v[134:135]
	v_mov_b64_e32 v[86:87], v[132:133]
	v_mov_b64_e32 v[84:85], v[130:131]
	s_branch .LBB0_972

; DI int crow(int reg, int h) { return (reg & 3) + 8 * (reg >> 2) + 4 * h; }
; #define MFMA32(a, b, c) __builtin_amdgcn_mfma_f32_32x32x16_bf16((a), (b), (c), 0, 0, 0)
;     DI bf16x8 kfrag_t(int tl, int kk) const { const int lane = threadIdx.x & 63; return ld8f_bf(krow(ck, nk, 32 * tl + (lane & 31)) + 16 * kk + 8 * (lane >> 5)); }
;     DI void init_s(f32x16& s, int) const { zero16(s); }
;     DI void init_s(f32x16& s, int) const { zero16(s); }
;     DI bf16x8 kfrag_t(int tl, int kk) const { const int lane = threadIdx.x & 63; return ld8f_bf(mk + ((size_t)(b * 256 + 32 * tl + (lane & 31)) * 4 + hd) * 128 + 16 * kk + 8 * (lane >> 5)); }
;     DI void init_s(f32x16& s, int) const { zero16(s); }
; template <class T> DI void attn_item(const T& t) {
;     ...
;     for (int c = cbeg; c < NCH; ++c) {
;         const int tl = t.tile(c);
;         if (!T::VSPLIT) {
; #pragma unroll
;             for (int s2 = 0; s2 < 2; ++s2)
; #pragma unroll
;                 for (int dd = 0; dd < D / 32; ++dd) vf[s2][dd] = t.vfrag_t(tl, s2, dd);
;         }
;         f32x16 s;
;         t.init_s(s, tl);
;         if (T::VSPLIT) {
; #pragma unroll
;             for (int kk = 0; kk < D / 16; ++kk) kf[kk] = t.kfrag_t(tl, kk);
;         }
; #pragma unroll
;         for (int kk = 0; kk < D / 16; ++kk) s = MFMA32(kf[kk], qf[kk], s);
;         if (!T::VSPLIT && c + 1 < NCH) {
; #pragma unroll
;             for (int kk = 0; kk < D / 16; ++kk) kf[kk] = t.kfrag_t(tl + 1, kk); }
;         t.post_s(s, tl, r, h);
;     DI void init_s(f32x16& s, int tl) const { const int h = (threadIdx.x & 63) >> 5; const float c0 = slope2 * (float)(32 * tl) - lc;
; #pragma unroll
;         for (int i = 0; i < 16; ++i) s[i] = slope2 * (float)crow(i, h) + c0; }
;     DI void post_s(f32x16& s, int tl, int r, int h) const {
;         if (tl == g - 4) {
; #pragma unroll
;             for (int i = 0; i < 16; ++i) s[i] = crow(i, h) > r ? s[i] : -INFINITY; }
.LBB0_972:
	v_cvt_f32_i32_e32 v36, s72
	s_cmp_eq_u32 s79, s40
	s_cselect_b64 s[76:77], -1, 0
	s_and_b64 vcc, exec, s[76:77]
	v_fma_f32 v36, v102, v36, -v124
	v_pk_add_f32 v[50:51], v[104:105], v[36:37] op_sel_hi:[1,0]
	v_pk_add_f32 v[48:49], v[106:107], v[36:37] op_sel_hi:[1,0]
	v_pk_add_f32 v[46:47], v[108:109], v[36:37] op_sel_hi:[1,0]
	v_pk_add_f32 v[44:45], v[110:111], v[36:37] op_sel_hi:[1,0]
	v_pk_add_f32 v[42:43], v[112:113], v[36:37] op_sel_hi:[1,0]
	v_pk_add_f32 v[40:41], v[114:115], v[36:37] op_sel_hi:[1,0]
	v_pk_add_f32 v[38:39], v[116:117], v[36:37] op_sel_hi:[1,0]
	v_pk_add_f32 v[36:37], v[118:119], v[36:37] op_sel_hi:[1,0]
	s_waitcnt vmcnt(4)
	s_nop 0
	v_mfma_f32_32x32x16_bf16 v[36:51], v[68:71], v[52:55], v[36:51]
	v_mfma_f32_32x32x16_bf16 v[36:51], v[72:75], v[56:59], v[36:51]
	v_mfma_f32_32x32x16_bf16 v[36:51], v[76:79], v[60:63], v[36:51]
	v_mfma_f32_32x32x16_bf16 v[36:51], v[80:83], v[64:67], v[36:51]
	s_cbranch_vccnz .LBB0_975
	v_lshl_add_u64 v[80:81], v[122:123], 0, s[40:41]
	global_load_dwordx4 v[68:71], v[80:81], off offset:-2048
	global_load_dwordx4 v[72:75], v[80:81], off offset:-1024
	global_load_dwordx4 v[76:79], v[80:81], off
	s_nop 0
	global_load_dwordx4 v[80:83], v[80:81], off offset:1024
	s_add_u32 s98, s40, 0x1000
	s_addc_u32 s99, s41, 0
	v_lshl_add_u64 v[146:147], v[120:121], 0, s[98:99]
	global_load_dwordx4 v[142:145], v[146:147], off offset:-2048
	global_load_dwordx4 v[138:141], v[146:147], off offset:-1536
	global_load_dwordx4 v[134:137], v[146:147], off
	global_load_dwordx4 v[130:133], v[146:147], off offset:512
	s_cmp_lg_u32 s85, s40
	s_cbranch_scc1 .LBB0_975
	s_nop 2
	v_cndmask_b32_e64 v36, v187, v36, s[6:7]
	v_cndmask_b32_e64 v37, v37, v187, s[8:9]
	v_cndmask_b32_e64 v38, v187, v38, s[10:11]
	v_cndmask_b32_e64 v39, v187, v39, s[12:13]
	v_cndmask_b32_e64 v40, v187, v40, s[14:15]
	v_cndmask_b32_e64 v41, v187, v41, s[16:17]
	v_cndmask_b32_e64 v42, v187, v42, s[18:19]
	v_cndmask_b32_e64 v43, v187, v43, s[20:21]
	v_cndmask_b32_e64 v44, v187, v44, s[22:23]
	v_cndmask_b32_e64 v45, v187, v45, s[24:25]
	v_cndmask_b32_e64 v46, v187, v46, s[26:27]
	v_cndmask_b32_e64 v47, v187, v47, s[28:29]
	v_cndmask_b32_e64 v48, v187, v48, s[30:31]
	v_cndmask_b32_e64 v49, v187, v49, s[34:35]
	v_cndmask_b32_e64 v50, v187, v50, s[36:37]
	v_cndmask_b32_e64 v51, v187, v51, s[38:39]

; DI float fexp2(float x) { return __builtin_amdgcn_exp2f(x); }
; DI bf16x8 pack_step(const f32x16& x, int s) { u32x4 p; p.x = pk2(x[8 * s], x[8 * s + 1]); p.y = pk2(x[8 * s + 2], x[8 * s + 3]); p.z = pk2(x[8 * s + 4], x[8 * s + 5]); p.w = pk2(x[8 * s + 6], x[8 * s + 7]); return __builtin_bit_cast(bf16x8, p); }
; #define MFMA32(a, b, c) __builtin_amdgcn_mfma_f32_32x32x16_bf16((a), (b), (c), 0, 0, 0)
;     DI bf16x8 kfrag_t(int tl, int kk) const { const int lane = threadIdx.x & 63; return ld8f_bf(krow(ck, nk, 32 * tl + (lane & 31)) + 16 * kk + 8 * (lane >> 5)); }
;     DI bf16x8 kfrag_t(int tl, int kk) const { const int lane = threadIdx.x & 63; return ld8f_bf(mk + ((size_t)(b * 256 + 32 * tl + (lane & 31)) * 4 + hd) * 128 + 16 * kk + 8 * (lane >> 5)); }
; template <class T> DI void attn_item(const T& t) {
;     ...
;     for (int kk = 0; kk < D / 16; ++kk) qf[kk] = t.qfrag(r, 16 * kk + 8 * h);
;     const int cbeg = t.cbeg();
;     if (!T::VSPLIT) {
; #pragma unroll
;         for (int kk = 0; kk < D / 16; ++kk) kf[kk] = t.kfrag_t(t.tile(cbeg), kk);
;     }
;     float m = t.m_init(r), l = t.l_init();
;     f32x16 o[D / 32];
; #pragma unroll
;     for (int dd = 0; dd < D / 32; ++dd)
; #pragma unroll
;         for (int i = 0; i < 16; ++i) o[dd][i] = 0.f;
;     bf16x8 vf[2][D / 32];
;     ...
;         float ps = 0.f;
; #pragma unroll
;         for (int i = 0; i < 16; ++i) { const float p = fexp2(s[i] - m); s[i] = p; ps += p; }
;         ps += __shfl_xor(ps, 32);
;         l += ps;
; #pragma unroll
;         for (int s2 = 0; s2 < 2; ++s2) { const bf16x8 pb = pack_step(s, s2);
;             if (T::VSPLIT) {
; #pragma unroll
;                 for (int dd = 0; dd < D / 32; ++dd) vf[s2][dd] = t.vfrag_t(tl, s2, dd);
;             }
; #pragma unroll
;             for (int dd = 0; dd < D / 32; ++dd) o[dd] = MFMA32(vf[s2][dd], pb, o[dd]); }
.LBB0_1078:
	s_mul_i32 s40, s74, 0xf20
	s_add_i32 s76, s40, s68
	s_addk_i32 s76, 0x2328
	s_cmpk_gt_i32 s76, 0x2fff
	s_mov_b64 s[40:41], -1
	s_cbranch_scc1 .LBB0_1069
	s_cmpk_gt_i32 s76, 0xfff
	v_lshlrev_b32_e32 v2, 1, v184
	s_cbranch_scc0 .LBB0_1090
	s_add_i32 s40, s76, 0xfffff000
	s_lshr_b32 s40, s40, 10
	s_and_b32 s84, s76, 0x7f
	s_lshl_b32 s41, s40, 12
	s_lshl_b32 s85, s84, 5
	s_or_b32 s41, s41, s85
	v_or_b32_e32 v4, s41, v185
	s_bfe_u32 s82, s76, 0x30007
	v_mul_lo_u32 v4, v4, s59
	v_mov_b32_e32 v5, v3
	v_lshl_add_u64 v[4:5], v[4:5], 1, s[48:49]
	s_lshl_b32 s74, s82, 7
	v_lshl_add_u64 v[100:101], v[4:5], 0, s[74:75]
	s_lshl_b32 s74, s82, 2
	v_mov_b32_e32 v4, s74
	v_lshl_add_u64 v[6:7], v[100:101], 0, v[2:3]
	global_load_dword v8, v4, s[72:73]
	global_load_dwordx4 v[52:55], v[6:7], off
	global_load_dwordx4 v[56:59], v[6:7], off offset:32
	global_load_dwordx4 v[60:63], v[6:7], off offset:64
	global_load_dwordx4 v[64:67], v[6:7], off offset:96
	v_sub_u32_e64 v6, 4, s84 clamp
	s_lshl_b32 s41, s76, 10
	v_add_u32_e32 v6, s84, v6
	s_and_b32 s41, s41, 0x80000
	s_lshl_b32 s40, s40, 20
	v_add_u32_e32 v6, -4, v6
	s_or_b32 s74, s40, s41
	v_ashrrev_i32_e32 v7, 31, v6
	v_lshl_add_u64 v[4:5], v[188:189], 0, s[74:75]
	v_lshlrev_b64 v[6:7], 12, v[6:7]
	v_lshl_add_u64 v[4:5], v[4:5], 0, v[6:7]
	global_load_dwordx4 v[80:83], v[4:5], off offset:3072
	global_load_dwordx4 v[76:79], v[4:5], off offset:2048
	global_load_dwordx4 v[72:75], v[4:5], off offset:1024
	global_load_dwordx4 v[68:71], v[4:5], off
	s_lshl_b32 s40, s77, 5
	s_lshl_b32 s69, s69, 5
	s_add_i32 s40, s40, s68
	s_sub_i32 s40, s40, s69
	s_add_i32 s40, s40, 40
	s_mov_b32 s41, s75
	s_and_b32 s40, s40, 0x7f
	v_and_b32_e32 v9, 64, v1
	s_add_i32 s82, s82, 1
	v_cmp_lt_u64_e64 s[68:69], s[40:41], 4
	v_xor_b32_e32 v7, 32, v1
	v_add_u32_e32 v9, 64, v9
	v_cvt_f32_ubyte0_e32 v10, s82
	s_and_b64 s[68:69], s[68:69], exec
	v_or_b32_e32 v11, s85, v185
	v_cmp_lt_i32_e32 vcc, v7, v9
	v_exp_f32_e64 v9, -v10
	s_cselect_b32 s40, s40, 4
	s_min_u32 s68, s84, 4
	v_cvt_f32_u32_e32 v10, v11
	s_lshl_b32 s77, s40, 12
	s_sub_i32 s40, s84, s68
	s_ashr_i32 s41, s40, 31
	s_add_u32 s82, s77, 0xffffc000
	s_add_u32 s84, s77, 0x1000
	s_lshl_b64 s[40:41], s[40:41], 12
	v_cndmask_b32_e32 v7, v1, v7, vcc
	v_mul_f32_e32 v102, 0x3fb8aa3b, v9
	s_add_u32 s40, s40, s74
	v_mov_b32_e32 v18, v3
	v_mov_b32_e32 v19, v3
	v_mov_b32_e32 v4, v3
	v_mov_b32_e32 v5, v3
	v_mov_b32_e32 v6, v3
	v_lshlrev_b32_e32 v103, 2, v7
	v_mul_f32_e32 v124, v102, v10
	s_addc_u32 s41, s41, 0
	s_lshl_b32 s68, s68, 5
	v_mov_b32_e32 v7, v3
	v_mov_b32_e32 v9, v3
	v_mov_b32_e32 v10, v3
	v_mov_b32_e32 v11, v3
	v_mov_b32_e32 v12, v3
	v_mov_b32_e32 v13, v3
	v_mov_b32_e32 v14, v3
	v_mov_b32_e32 v15, v3
	v_mov_b32_e32 v16, v3
	v_mov_b32_e32 v17, v3
	v_pk_mul_f32 v[104:105], v[102:103], v[190:191] op_sel_hi:[0,1]
	v_pk_mul_f32 v[106:107], v[102:103], v[192:193] op_sel_hi:[0,1]
	v_pk_mul_f32 v[108:109], v[102:103], v[194:195] op_sel_hi:[0,1]
	v_pk_mul_f32 v[110:111], v[102:103], v[196:197] op_sel_hi:[0,1]
	v_pk_mul_f32 v[112:113], v[102:103], v[198:199] op_sel_hi:[0,1]
	v_pk_mul_f32 v[114:115], v[102:103], v[200:201] op_sel_hi:[0,1]
	v_pk_mul_f32 v[116:117], v[102:103], v[202:203] op_sel_hi:[0,1]
	v_pk_mul_f32 v[118:119], v[102:103], v[204:205] op_sel_hi:[0,1]
	v_lshl_add_u64 v[120:121], v[208:209], 0, s[40:41]
	s_sub_i32 s74, s85, s68
	v_lshl_add_u64 v[122:123], v[212:213], 0, s[40:41]
	v_mov_b32_e32 v125, 1.0
	s_mov_b64 s[40:41], 0
	s_waitcnt vmcnt(8)
	v_mul_f32_e32 v126, 0x3fb8aa3b, v8
	v_mov_b32_e32 v8, v3
	v_mov_b64_e32 v[34:35], v[18:19]
	v_mov_b64_e32 v[32:33], v[16:17]
	v_mov_b64_e32 v[30:31], v[14:15]
	v_mov_b64_e32 v[28:29], v[12:13]
	v_mov_b64_e32 v[26:27], v[10:11]
	v_mov_b64_e32 v[24:25], v[8:9]
	v_mov_b64_e32 v[22:23], v[6:7]
	v_mov_b64_e32 v[20:21], v[4:5]
	v_lshl_add_u64 v[84:85], v[120:121], 0, s[40:41]
	global_load_dwordx4 v[96:99], v[84:85], off offset:-2048
	global_load_dwordx4 v[92:95], v[84:85], off offset:-1536
	global_load_dwordx4 v[88:91], v[84:85], off
	s_nop 0
	global_load_dwordx4 v[84:87], v[84:85], off offset:512
	s_branch .LBB0_1082
.LBB0_1081:
	s_cmp_eq_u32 s77, s40
	s_cbranch_scc1 .Latt_sw4_last
	v_sub_f32_e32 v36, v36, v126
	v_exp_f32_e32 v36, v36
	v_sub_f32_e32 v37, v37, v126
	v_exp_f32_e32 v37, v37
	v_sub_f32_e32 v38, v38, v126
	v_exp_f32_e32 v38, v38
	v_sub_f32_e32 v39, v39, v126
	v_exp_f32_e32 v39, v39
	v_sub_f32_e32 v40, v40, v126
	v_add_f32_e32 v127, 0, v36
	v_exp_f32_e32 v40, v40
	v_sub_f32_e32 v41, v41, v126
	v_add_f32_e32 v127, v37, v127
	v_exp_f32_e32 v41, v41
	v_sub_f32_e32 v42, v42, v126
	v_sub_f32_e32 v43, v43, v126
	v_add_f32_e32 v127, v38, v127
	v_exp_f32_e32 v42, v42
	v_exp_f32_e32 v43, v43
	v_add_f32_e32 v127, v39, v127
	v_sub_f32_e32 v44, v44, v126
	v_add_f32_e32 v127, v40, v127
	v_exp_f32_e32 v44, v44
	v_sub_f32_e32 v45, v45, v126
	v_add_f32_e32 v127, v41, v127
	v_exp_f32_e32 v45, v45
	v_sub_f32_e32 v46, v46, v126
	v_add_f32_e32 v127, v42, v127
	v_exp_f32_e32 v46, v46
	v_sub_f32_e32 v47, v47, v126
	v_cvt_pk_bf16_f32 v36, v36, v37
	v_cvt_pk_bf16_f32 v37, v38, v39
	v_cvt_pk_bf16_f32 v38, v40, v41
	v_cvt_pk_bf16_f32 v39, v42, v43
	v_add_f32_e32 v127, v43, v127
	v_exp_f32_e32 v47, v47
	v_sub_f32_e32 v48, v48, v126
	s_waitcnt vmcnt(11)
	v_mfma_f32_32x32x16_bf16 v[20:35], v[96:99], v[36:39], v[20:35]
	v_add_f32_e32 v127, v44, v127
	v_exp_f32_e32 v40, v48
	v_sub_f32_e32 v41, v49, v126
	v_add_f32_e32 v127, v45, v127
	v_exp_f32_e32 v41, v41
	v_sub_f32_e32 v42, v50, v126
	v_add_f32_e32 v127, v46, v127
	s_waitcnt vmcnt(10)
	v_mfma_f32_32x32x16_bf16 v[4:19], v[92:95], v[36:39], v[4:19]
	v_sub_f32_e32 v36, v51, v126
	v_exp_f32_e32 v42, v42
	v_exp_f32_e32 v48, v36
	v_add_f32_e32 v127, v47, v127
	v_add_f32_e32 v43, v40, v127
	v_add_f32_e32 v43, v41, v43
	v_add_f32_e32 v43, v42, v43
	v_cvt_pk_bf16_f32 v36, v44, v45
	v_cvt_pk_bf16_f32 v37, v46, v47
	v_cvt_pk_bf16_f32 v38, v40, v41
	v_cvt_pk_bf16_f32 v39, v42, v48
	v_add_f32_e32 v40, v48, v43
	ds_bpermute_b32 v41, v103, v40
	s_waitcnt vmcnt(9)
	v_mfma_f32_32x32x16_bf16 v[20:35], v[88:91], v[36:39], v[20:35]
	s_add_u32 s40, s40, 0x1000
	s_addc_u32 s41, s41, 0
	s_add_i32 s74, s74, 32
	s_waitcnt lgkmcnt(0)
	v_add_f32_e32 v40, v40, v41
	s_cmp_eq_u32 s84, s40
	v_add_f32_e32 v125, v125, v40
	s_waitcnt vmcnt(8)
	v_mfma_f32_32x32x16_bf16 v[4:19], v[84:87], v[36:39], v[4:19]
	s_waitcnt vmcnt(0)
	s_nop 7
	v_mov_b64_e32 v[98:99], v[144:145]
	v_mov_b64_e32 v[96:97], v[142:143]
	v_mov_b64_e32 v[94:95], v[140:141]
	v_mov_b64_e32 v[92:93], v[138:139]
	v_mov_b64_e32 v[90:91], v[136:137]
	v_mov_b64_e32 v[88:89], v[134:135]
	v_mov_b64_e32 v[86:87], v[132:133]
	v_mov_b64_e32 v[84:85], v[130:131]
	s_branch .LBB0_1082

; DI int crow(int reg, int h) { return (reg & 3) + 8 * (reg >> 2) + 4 * h; }
; #define MFMA32(a, b, c) __builtin_amdgcn_mfma_f32_32x32x16_bf16((a), (b), (c), 0, 0, 0)
;     DI bf16x8 kfrag_t(int tl, int kk) const { const int lane = threadIdx.x & 63; return ld8f_bf(krow(ck, nk, 32 * tl + (lane & 31)) + 16 * kk + 8 * (lane >> 5)); }
;     DI void init_s(f32x16& s, int) const { zero16(s); }
;     DI void init_s(f32x16& s, int) const { zero16(s); }
;     DI bf16x8 kfrag_t(int tl, int kk) const { const int lane = threadIdx.x & 63; return ld8f_bf(mk + ((size_t)(b * 256 + 32 * tl + (lane & 31)) * 4 + hd) * 128 + 16 * kk + 8 * (lane >> 5)); }
;     DI void init_s(f32x16& s, int) const { zero16(s); }
; template <class T> DI void attn_item(const T& t) {
;     ...
;     for (int c = cbeg; c < NCH; ++c) {
;         const int tl = t.tile(c);
;         if (!T::VSPLIT) {
; #pragma unroll
;             for (int s2 = 0; s2 < 2; ++s2)
; #pragma unroll
;                 for (int dd = 0; dd < D / 32; ++dd) vf[s2][dd] = t.vfrag_t(tl, s2, dd);
;         }
;         f32x16 s;
;         t.init_s(s, tl);
;         if (T::VSPLIT) {
; #pragma unroll
;             for (int kk = 0; kk < D / 16; ++kk) kf[kk] = t.kfrag_t(tl, kk);
;         }
; #pragma unroll
;         for (int kk = 0; kk < D / 16; ++kk) s = MFMA32(kf[kk], qf[kk], s);
;         if (!T::VSPLIT && c + 1 < NCH) {
; #pragma unroll
;             for (int kk = 0; kk < D / 16; ++kk) kf[kk] = t.kfrag_t(tl + 1, kk); }
;         t.post_s(s, tl, r, h);
;     DI void init_s(f32x16& s, int tl) const { const int h = (threadIdx.x & 63) >> 5; const float c0 = slope2 * (float)(32 * tl) - lc;
; #pragma unroll
;         for (int i = 0; i < 16; ++i) s[i] = slope2 * (float)crow(i, h) + c0; }
;     DI void post_s(f32x16& s, int tl, int r, int h) const {
;         if (tl == g - 4) {
; #pragma unroll
;             for (int i = 0; i < 16; ++i) s[i] = crow(i, h) > r ? s[i] : -INFINITY; }
.LBB0_1082:
	v_cvt_f32_i32_e32 v36, s74
	s_cmp_eq_u32 s77, s40
	s_cselect_b64 s[68:69], -1, 0
	s_and_b64 vcc, exec, s[68:69]
	v_fma_f32 v36, v102, v36, -v124
	v_pk_add_f32 v[50:51], v[104:105], v[36:37] op_sel_hi:[1,0]
	v_pk_add_f32 v[48:49], v[106:107], v[36:37] op_sel_hi:[1,0]
	v_pk_add_f32 v[46:47], v[108:109], v[36:37] op_sel_hi:[1,0]
	v_pk_add_f32 v[44:45], v[110:111], v[36:37] op_sel_hi:[1,0]
	v_pk_add_f32 v[42:43], v[112:113], v[36:37] op_sel_hi:[1,0]
	v_pk_add_f32 v[40:41], v[114:115], v[36:37] op_sel_hi:[1,0]
	v_pk_add_f32 v[38:39], v[116:117], v[36:37] op_sel_hi:[1,0]
	v_pk_add_f32 v[36:37], v[118:119], v[36:37] op_sel_hi:[1,0]
	s_waitcnt vmcnt(4)
	s_nop 0
	v_mfma_f32_32x32x16_bf16 v[36:51], v[68:71], v[52:55], v[36:51]
	v_mfma_f32_32x32x16_bf16 v[36:51], v[72:75], v[56:59], v[36:51]
	v_mfma_f32_32x32x16_bf16 v[36:51], v[76:79], v[60:63], v[36:51]
	v_mfma_f32_32x32x16_bf16 v[36:51], v[80:83], v[64:67], v[36:51]
	s_cbranch_vccnz .LBB0_1085
	v_lshl_add_u64 v[80:81], v[122:123], 0, s[40:41]
	global_load_dwordx4 v[68:71], v[80:81], off offset:-2048
	global_load_dwordx4 v[72:75], v[80:81], off offset:-1024
	global_load_dwordx4 v[76:79], v[80:81], off
	s_nop 0
	global_load_dwordx4 v[80:83], v[80:81], off offset:1024
	s_add_u32 s98, s40, 0x1000
	s_addc_u32 s99, s41, 0
	v_lshl_add_u64 v[146:147], v[120:121], 0, s[98:99]
	global_load_dwordx4 v[142:145], v[146:147], off offset:-2048
	global_load_dwordx4 v[138:141], v[146:147], off offset:-1536
	global_load_dwordx4 v[134:137], v[146:147], off
	global_load_dwordx4 v[130:133], v[146:147], off offset:512
	s_cmp_lg_u32 s82, s40
	s_cbranch_scc1 .LBB0_1085
	s_nop 2
	v_cndmask_b32_e64 v36, v187, v36, s[6:7]
	v_cndmask_b32_e64 v37, v37, v187, s[8:9]
	v_cndmask_b32_e64 v38, v187, v38, s[10:11]
	v_cndmask_b32_e64 v39, v187, v39, s[12:13]
	v_cndmask_b32_e64 v40, v187, v40, s[14:15]
	v_cndmask_b32_e64 v41, v187, v41, s[16:17]
	v_cndmask_b32_e64 v42, v187, v42, s[18:19]
	v_cndmask_b32_e64 v43, v187, v43, s[20:21]
	v_cndmask_b32_e64 v44, v187, v44, s[22:23]
	v_cndmask_b32_e64 v45, v187, v45, s[24:25]
	v_cndmask_b32_e64 v46, v187, v46, s[26:27]
	v_cndmask_b32_e64 v47, v187, v47, s[28:29]
	v_cndmask_b32_e64 v48, v187, v48, s[30:31]
	v_cndmask_b32_e64 v49, v187, v49, s[34:35]
	v_cndmask_b32_e64 v50, v187, v50, s[36:37]
	v_cndmask_b32_e64 v51, v187, v51, s[38:39]
